# w_out epilogue: nt hint on the f32 residual-stream loads and stores (streamed once per layer), h and partial stores unchanged
# speedup vs baseline: 1.0144x; 1.0144x over previous
;     __device__ __forceinline__ void load(Ld& d, int row, int c0, int, int) const {
;         const int b = row / LP, t = row - b * LP - PADF;
;         const f32x4 z = (f32x4){0.f, 0.f, 0.f, 0.f}; d.v[0] = z; d.v[1] = z; d.v[2] = z; d.v[3] = z;
;         if (t >= 0) { const float* sr = xin ? ((t < NMETA) ? metain + (size_t)t * DM : xin + ((size_t)b * SEQ + (t - NMETA)) * DM) : hres_row(out, metah, row);
;             d.v[0] = *(const f32x4*)(sr + c0); d.v[1] = *(const f32x4*)(sr + c0 + 4); d.v[2] = *(const f32x4*)(sr + c0 + 128); d.v[3] = *(const f32x4*)(sr + c0 + 132); }
.LBB0_450:
	v_lshlrev_b64 v[134:135], 12, v[134:135]
	v_lshl_add_u64 v[134:135], v[136:137], 0, v[134:135]
	v_lshl_add_u64 v[134:135], v[204:205], 2, v[134:135]
	global_load_dwordx4 v[150:153], v[134:135], off offset:16 nt
	global_load_dwordx4 v[158:161], v[134:135], off nt
	global_load_dwordx4 v[154:157], v[134:135], off offset:528 nt
	global_load_dwordx4 v[162:165], v[134:135], off offset:512 nt

;     __device__ __forceinline__ void load(Ld& d, int row, int c0, int, int) const {
;         const int b = row / LP, t = row - b * LP - PADF;
;         const f32x4 z = (f32x4){0.f, 0.f, 0.f, 0.f}; d.v[0] = z; d.v[1] = z; d.v[2] = z; d.v[3] = z;
;         if (t >= 0) { const float* sr = xin ? ((t < NMETA) ? metain + (size_t)t * DM : xin + ((size_t)b * SEQ + (t - NMETA)) * DM) : hres_row(out, metah, row);
;             d.v[0] = *(const f32x4*)(sr + c0); d.v[1] = *(const f32x4*)(sr + c0 + 4); d.v[2] = *(const f32x4*)(sr + c0 + 128); d.v[3] = *(const f32x4*)(sr + c0 + 132); }
.LBB0_462:
	v_lshlrev_b64 v[134:135], 12, v[136:137]
	v_lshl_add_u64 v[134:135], v[138:139], 0, v[134:135]
	v_lshl_add_u64 v[146:147], v[204:205], 2, v[134:135]
	global_load_dwordx4 v[134:137], v[146:147], off offset:16 nt
	global_load_dwordx4 v[142:145], v[146:147], off nt
	global_load_dwordx4 v[138:141], v[146:147], off offset:528 nt
	s_nop 0
	global_load_dwordx4 v[146:149], v[146:147], off offset:512 nt

;     __device__ __forceinline__ void apply(const Ld& d, int row, int c0, int, int, int, const f32x4& a0, const f32x4& b0, const f32x4& a1, const f32x4& b1) const { half(d.g0, row, c0, a0, b0); half(d.g1, row, c0 + 128, a1, b1); }
;     __device__ __forceinline__ void apply(const Ld& d, int row, int c0, int, int, int, const f32x4& a0, const f32x4& b0, const f32x4& a1, const f32x4& b1) const { half(d.g0, d.p0, row, c0, a0, b0); half(d.g1, d.p1, row, c0 + 128, a1, b1); }
;     __device__ __forceinline__ void apply(const Ld& d, int row, int c0, int pn, int wc, int fq, const f32x4& a0, const f32x4& b0, const f32x4& a1, const f32x4& b1) const {
;         float* r = hres_row(out, metah, row);
;         f32x4 v0 = (f32x4){0.f, 0.f, 0.f, 0.f}, v1 = v0, v2 = v0, v3 = v0;
;         if (r) { v0 = d.v[0] + a0; v1 = d.v[1] + b0; v2 = d.v[2] + a1; v3 = d.v[3] + b1;
;             *(f32x4*)(r + c0) = v0; *(f32x4*)(r + c0 + 4) = v1; *(f32x4*)(r + c0 + 128) = v2; *(f32x4*)(r + c0 + 132) = v3; }
.LBB0_469:
	s_or_b64 exec, exec, s[0:1]
	v_cmp_ne_u64_e32 vcc, 0, v[208:209]
	v_mov_b32_e32 v166, 0
	v_mov_b32_e32 v167, 0
	v_mov_b32_e32 v168, 0
	v_mov_b32_e32 v169, 0
	v_mov_b32_e32 v170, 0
	v_mov_b32_e32 v171, 0
	v_mov_b32_e32 v172, 0
	v_mov_b32_e32 v173, 0
	v_mov_b32_e32 v174, 0
	v_mov_b32_e32 v175, 0
	v_mov_b32_e32 v176, 0
	v_mov_b32_e32 v177, 0
	v_mov_b32_e32 v178, 0
	v_mov_b32_e32 v179, 0
	v_mov_b32_e32 v180, 0
	v_mov_b32_e32 v181, 0
	s_and_saveexec_b64 s[0:1], vcc
	s_cbranch_execz .LBB0_471
	s_waitcnt vmcnt(0)
	v_pk_add_f32 v[180:181], v[132:133], v[160:161]
	v_pk_add_f32 v[178:179], v[130:131], v[158:159]
	v_pk_add_f32 v[176:177], v[128:129], v[152:153]
	v_pk_add_f32 v[174:175], v[126:127], v[150:151]
	v_pk_add_f32 v[172:173], v[124:125], v[164:165]
	v_pk_add_f32 v[170:171], v[122:123], v[162:163]
	v_pk_add_f32 v[168:169], v[120:121], v[156:157]
	v_pk_add_f32 v[166:167], v[118:119], v[154:155]
	v_lshl_add_u64 v[150:151], v[204:205], 2, v[208:209]
	global_store_dwordx4 v[150:151], v[178:181], off nt
	global_store_dwordx4 v[150:151], v[174:177], off offset:16 nt
	global_store_dwordx4 v[150:151], v[170:173], off offset:512 nt
	global_store_dwordx4 v[150:151], v[166:169], off offset:528 nt

;     __device__ __forceinline__ void apply(const Ld& d, int row, int c0, int, int, int, const f32x4& a0, const f32x4& b0, const f32x4& a1, const f32x4& b1) const { half(d.g0, row, c0, a0, b0); half(d.g1, row, c0 + 128, a1, b1); }
;     __device__ __forceinline__ void apply(const Ld& d, int row, int c0, int, int, int, const f32x4& a0, const f32x4& b0, const f32x4& a1, const f32x4& b1) const { half(d.g0, d.p0, row, c0, a0, b0); half(d.g1, d.p1, row, c0 + 128, a1, b1); }
;     __device__ __forceinline__ void apply(const Ld& d, int row, int c0, int pn, int wc, int fq, const f32x4& a0, const f32x4& b0, const f32x4& a1, const f32x4& b1) const {
;         float* r = hres_row(out, metah, row);
;         f32x4 v0 = (f32x4){0.f, 0.f, 0.f, 0.f}, v1 = v0, v2 = v0, v3 = v0;
;         if (r) { v0 = d.v[0] + a0; v1 = d.v[1] + b0; v2 = d.v[2] + a1; v3 = d.v[3] + b1;
;             *(f32x4*)(r + c0) = v0; *(f32x4*)(r + c0 + 4) = v1; *(f32x4*)(r + c0 + 128) = v2; *(f32x4*)(r + c0 + 132) = v3; }
.LBB0_481:
	s_or_b64 exec, exec, s[0:1]
	v_cmp_ne_u64_e32 vcc, 0, v[168:169]
	v_mov_b32_e32 v150, 0
	v_mov_b32_e32 v151, 0
	v_mov_b32_e32 v152, 0
	v_mov_b32_e32 v153, 0
	v_mov_b32_e32 v154, 0
	v_mov_b32_e32 v155, 0
	v_mov_b32_e32 v156, 0
	v_mov_b32_e32 v157, 0
	v_mov_b32_e32 v158, 0
	v_mov_b32_e32 v159, 0
	v_mov_b32_e32 v160, 0
	v_mov_b32_e32 v161, 0
	v_mov_b32_e32 v162, 0
	v_mov_b32_e32 v163, 0
	v_mov_b32_e32 v164, 0
	v_mov_b32_e32 v165, 0
	s_and_saveexec_b64 s[0:1], vcc
	s_cbranch_execz .LBB0_483
	v_pk_add_f32 v[164:165], v[116:117], v[144:145]
	v_pk_add_f32 v[162:163], v[114:115], v[142:143]
	v_pk_add_f32 v[160:161], v[112:113], v[136:137]
	v_pk_add_f32 v[158:159], v[110:111], v[134:135]
	v_pk_add_f32 v[156:157], v[108:109], v[148:149]
	v_pk_add_f32 v[154:155], v[106:107], v[146:147]
	v_pk_add_f32 v[152:153], v[104:105], v[140:141]
	v_pk_add_f32 v[150:151], v[102:103], v[138:139]
	v_lshl_add_u64 v[134:135], v[204:205], 2, v[168:169]
	global_store_dwordx4 v[134:135], v[162:165], off nt
	global_store_dwordx4 v[134:135], v[158:161], off offset:16 nt
	global_store_dwordx4 v[134:135], v[154:157], off offset:512 nt
	global_store_dwordx4 v[134:135], v[150:153], off offset:528 nt

;     __device__ __forceinline__ void load(Ld& d, int row, int c0, int, int) const {
;         const int b = row / LP, t = row - b * LP - PADF;
;         const f32x4 z = (f32x4){0.f, 0.f, 0.f, 0.f}; d.v[0] = z; d.v[1] = z; d.v[2] = z; d.v[3] = z;
;         if (t >= 0) { const float* sr = xin ? ((t < NMETA) ? metain + (size_t)t * DM : xin + ((size_t)b * SEQ + (t - NMETA)) * DM) : hres_row(out, metah, row);
;             d.v[0] = *(const f32x4*)(sr + c0); d.v[1] = *(const f32x4*)(sr + c0 + 4); d.v[2] = *(const f32x4*)(sr + c0 + 128); d.v[3] = *(const f32x4*)(sr + c0 + 132); }
.LBB0_498:
	v_lshlrev_b64 v[134:135], 12, v[136:137]
	v_lshl_add_u64 v[134:135], v[138:139], 0, v[134:135]
	v_lshl_add_u64 v[134:135], v[204:205], 2, v[134:135]
	global_load_dwordx4 v[150:153], v[134:135], off offset:16 nt
	global_load_dwordx4 v[158:161], v[134:135], off nt
	global_load_dwordx4 v[154:157], v[134:135], off offset:528 nt
	global_load_dwordx4 v[162:165], v[134:135], off offset:512 nt

;     __device__ __forceinline__ void load(Ld& d, int row, int c0, int, int) const {
;         const int b = row / LP, t = row - b * LP - PADF;
;         const f32x4 z = (f32x4){0.f, 0.f, 0.f, 0.f}; d.v[0] = z; d.v[1] = z; d.v[2] = z; d.v[3] = z;
;         if (t >= 0) { const float* sr = xin ? ((t < NMETA) ? metain + (size_t)t * DM : xin + ((size_t)b * SEQ + (t - NMETA)) * DM) : hres_row(out, metah, row);
;             d.v[0] = *(const f32x4*)(sr + c0); d.v[1] = *(const f32x4*)(sr + c0 + 4); d.v[2] = *(const f32x4*)(sr + c0 + 128); d.v[3] = *(const f32x4*)(sr + c0 + 132); }
;     }
.LBB0_510:
	v_lshlrev_b64 v[134:135], 12, v[134:135]
	v_lshl_add_u64 v[134:135], v[136:137], 0, v[134:135]
	v_lshl_add_u64 v[146:147], v[204:205], 2, v[134:135]
	global_load_dwordx4 v[134:137], v[146:147], off offset:16 nt
	global_load_dwordx4 v[142:145], v[146:147], off nt
	global_load_dwordx4 v[138:141], v[146:147], off offset:528 nt
	s_nop 0
	global_load_dwordx4 v[146:149], v[146:147], off offset:512 nt

;     __device__ __forceinline__ void apply(const Ld& d, int row, int c0, int pn, int wc, int fq, const f32x4& a0, const f32x4& b0, const f32x4& a1, const f32x4& b1) const {
;         float* r = hres_row(out, metah, row);
;         f32x4 v0 = (f32x4){0.f, 0.f, 0.f, 0.f}, v1 = v0, v2 = v0, v3 = v0;
;         if (r) { v0 = d.v[0] + a0; v1 = d.v[1] + b0; v2 = d.v[2] + a1; v3 = d.v[3] + b1;
;             *(f32x4*)(r + c0) = v0; *(f32x4*)(r + c0 + 4) = v1; *(f32x4*)(r + c0 + 128) = v2; *(f32x4*)(r + c0 + 132) = v3; }
.LBB0_517:
	s_or_b64 exec, exec, s[0:1]
	v_cmp_ne_u64_e32 vcc, 0, v[210:211]
	v_mov_b32_e32 v166, 0
	v_mov_b32_e32 v167, 0
	v_mov_b32_e32 v168, 0
	v_mov_b32_e32 v169, 0
	v_mov_b32_e32 v170, 0
	v_mov_b32_e32 v171, 0
	v_mov_b32_e32 v172, 0
	v_mov_b32_e32 v173, 0
	v_mov_b32_e32 v174, 0
	v_mov_b32_e32 v175, 0
	v_mov_b32_e32 v176, 0
	v_mov_b32_e32 v177, 0
	v_mov_b32_e32 v178, 0
	v_mov_b32_e32 v179, 0
	v_mov_b32_e32 v180, 0
	v_mov_b32_e32 v181, 0
	s_and_saveexec_b64 s[0:1], vcc
	s_cbranch_execz .LBB0_519
	s_waitcnt vmcnt(0)
	v_pk_add_f32 v[180:181], v[100:101], v[160:161]
	v_pk_add_f32 v[178:179], v[98:99], v[158:159]
	v_pk_add_f32 v[176:177], v[96:97], v[152:153]
	v_pk_add_f32 v[174:175], v[94:95], v[150:151]
	v_pk_add_f32 v[172:173], v[92:93], v[164:165]
	v_pk_add_f32 v[170:171], v[90:91], v[162:163]
	v_pk_add_f32 v[168:169], v[88:89], v[156:157]
	v_pk_add_f32 v[166:167], v[86:87], v[154:155]
	v_lshl_add_u64 v[150:151], v[204:205], 2, v[210:211]
	global_store_dwordx4 v[150:151], v[178:181], off nt
	global_store_dwordx4 v[150:151], v[174:177], off offset:16 nt
	global_store_dwordx4 v[150:151], v[170:173], off offset:512 nt
	global_store_dwordx4 v[150:151], v[166:169], off offset:528 nt

;     __device__ __forceinline__ void apply(const Ld& d, int row, int c0, int pn, int wc, int fq, const f32x4& a0, const f32x4& b0, const f32x4& a1, const f32x4& b1) const {
;         float* r = hres_row(out, metah, row);
;         f32x4 v0 = (f32x4){0.f, 0.f, 0.f, 0.f}, v1 = v0, v2 = v0, v3 = v0;
;         if (r) { v0 = d.v[0] + a0; v1 = d.v[1] + b0; v2 = d.v[2] + a1; v3 = d.v[3] + b1;
;             *(f32x4*)(r + c0) = v0; *(f32x4*)(r + c0 + 4) = v1; *(f32x4*)(r + c0 + 128) = v2; *(f32x4*)(r + c0 + 132) = v3; }
.LBB0_529:
	s_or_b64 exec, exec, s[0:1]
	v_cmp_ne_u64_e32 vcc, 0, v[168:169]
	v_mov_b32_e32 v150, 0
	v_mov_b32_e32 v151, 0
	v_mov_b32_e32 v152, 0
	v_mov_b32_e32 v153, 0
	v_mov_b32_e32 v154, 0
	v_mov_b32_e32 v155, 0
	v_mov_b32_e32 v156, 0
	v_mov_b32_e32 v157, 0
	v_mov_b32_e32 v158, 0
	v_mov_b32_e32 v159, 0
	v_mov_b32_e32 v160, 0
	v_mov_b32_e32 v161, 0
	v_mov_b32_e32 v162, 0
	v_mov_b32_e32 v163, 0
	v_mov_b32_e32 v164, 0
	v_mov_b32_e32 v165, 0
	s_and_saveexec_b64 s[0:1], vcc
	s_cbranch_execz .LBB0_531
	v_pk_add_f32 v[164:165], v[84:85], v[144:145]
	v_pk_add_f32 v[162:163], v[82:83], v[142:143]
	v_pk_add_f32 v[160:161], v[80:81], v[136:137]
	v_pk_add_f32 v[158:159], v[78:79], v[134:135]
	v_pk_add_f32 v[156:157], v[76:77], v[148:149]
	v_pk_add_f32 v[154:155], v[74:75], v[146:147]
	v_pk_add_f32 v[152:153], v[72:73], v[140:141]
	v_pk_add_f32 v[150:151], v[70:71], v[138:139]
	v_lshl_add_u64 v[134:135], v[204:205], 2, v[168:169]
	global_store_dwordx4 v[134:135], v[162:165], off nt
	global_store_dwordx4 v[134:135], v[158:161], off offset:16 nt
	global_store_dwordx4 v[134:135], v[154:157], off offset:512 nt
	global_store_dwordx4 v[134:135], v[150:153], off offset:528 nt

;     __device__ __forceinline__ void apply(const Ld& d, int row, int c0, int pn, int wc, int fq, const f32x4& a0, const f32x4& b0, const f32x4& a1, const f32x4& b1) const {
;         float* r = hres_row(out, metah, row);
;         f32x4 v0 = (f32x4){0.f, 0.f, 0.f, 0.f}, v1 = v0, v2 = v0, v3 = v0;
;         if (r) { v0 = d.v[0] + a0; v1 = d.v[1] + b0; v2 = d.v[2] + a1; v3 = d.v[3] + b1;
;             *(f32x4*)(r + c0) = v0; *(f32x4*)(r + c0 + 4) = v1; *(f32x4*)(r + c0 + 128) = v2; *(f32x4*)(r + c0 + 132) = v3; }
.LBB0_565:
	s_or_b64 exec, exec, s[0:1]
	v_cmp_ne_u64_e32 vcc, 0, v[210:211]
	v_mov_b32_e32 v166, 0
	v_mov_b32_e32 v167, 0
	v_mov_b32_e32 v168, 0
	v_mov_b32_e32 v169, 0
	v_mov_b32_e32 v170, 0
	v_mov_b32_e32 v171, 0
	v_mov_b32_e32 v172, 0
	v_mov_b32_e32 v173, 0
	v_mov_b32_e32 v174, 0
	v_mov_b32_e32 v175, 0
	v_mov_b32_e32 v176, 0
	v_mov_b32_e32 v177, 0
	v_mov_b32_e32 v178, 0
	v_mov_b32_e32 v179, 0
	v_mov_b32_e32 v180, 0
	v_mov_b32_e32 v181, 0
	s_and_saveexec_b64 s[0:1], vcc
	s_cbranch_execz .LBB0_567
	s_waitcnt vmcnt(0)
	v_pk_add_f32 v[180:181], v[68:69], v[160:161]
	v_pk_add_f32 v[178:179], v[66:67], v[158:159]
	v_pk_add_f32 v[176:177], v[64:65], v[152:153]
	v_pk_add_f32 v[174:175], v[62:63], v[150:151]
	v_pk_add_f32 v[172:173], v[60:61], v[164:165]
	v_pk_add_f32 v[170:171], v[58:59], v[162:163]
	v_pk_add_f32 v[168:169], v[56:57], v[156:157]
	v_pk_add_f32 v[166:167], v[54:55], v[154:155]
	v_lshl_add_u64 v[150:151], v[204:205], 2, v[210:211]
	global_store_dwordx4 v[150:151], v[178:181], off nt
	global_store_dwordx4 v[150:151], v[174:177], off offset:16 nt
	global_store_dwordx4 v[150:151], v[170:173], off offset:512 nt
	global_store_dwordx4 v[150:151], v[166:169], off offset:528 nt

;     __device__ __forceinline__ void apply(const Ld& d, int row, int c0, int pn, int wc, int fq, const f32x4& a0, const f32x4& b0, const f32x4& a1, const f32x4& b1) const {
;         float* r = hres_row(out, metah, row);
;         f32x4 v0 = (f32x4){0.f, 0.f, 0.f, 0.f}, v1 = v0, v2 = v0, v3 = v0;
;         if (r) { v0 = d.v[0] + a0; v1 = d.v[1] + b0; v2 = d.v[2] + a1; v3 = d.v[3] + b1;
;             *(f32x4*)(r + c0) = v0; *(f32x4*)(r + c0 + 4) = v1; *(f32x4*)(r + c0 + 128) = v2; *(f32x4*)(r + c0 + 132) = v3; }
.LBB0_577:
	s_or_b64 exec, exec, s[0:1]
	v_cmp_ne_u64_e32 vcc, 0, v[168:169]
	v_mov_b32_e32 v150, 0
	v_mov_b32_e32 v151, 0
	v_mov_b32_e32 v152, 0
	v_mov_b32_e32 v153, 0
	v_mov_b32_e32 v154, 0
	v_mov_b32_e32 v155, 0
	v_mov_b32_e32 v156, 0
	v_mov_b32_e32 v157, 0
	v_mov_b32_e32 v158, 0
	v_mov_b32_e32 v159, 0
	v_mov_b32_e32 v160, 0
	v_mov_b32_e32 v161, 0
	v_mov_b32_e32 v162, 0
	v_mov_b32_e32 v163, 0
	v_mov_b32_e32 v164, 0
	v_mov_b32_e32 v165, 0
	s_and_saveexec_b64 s[0:1], vcc
	s_cbranch_execz .LBB0_579
	v_pk_add_f32 v[164:165], v[52:53], v[144:145]
	v_pk_add_f32 v[162:163], v[50:51], v[142:143]
	v_pk_add_f32 v[160:161], v[48:49], v[136:137]
	v_pk_add_f32 v[158:159], v[46:47], v[134:135]
	v_pk_add_f32 v[156:157], v[44:45], v[148:149]
	v_pk_add_f32 v[154:155], v[42:43], v[146:147]
	v_pk_add_f32 v[152:153], v[40:41], v[140:141]
	v_pk_add_f32 v[150:151], v[38:39], v[138:139]
	v_lshl_add_u64 v[134:135], v[204:205], 2, v[168:169]
	global_store_dwordx4 v[134:135], v[162:165], off nt
	global_store_dwordx4 v[134:135], v[158:161], off offset:16 nt
	global_store_dwordx4 v[134:135], v[154:157], off offset:512 nt
	global_store_dwordx4 v[134:135], v[150:153], off offset:528 nt

;     __device__ __forceinline__ void apply(const Ld& d, int row, int c0, int pn, int wc, int fq, const f32x4& a0, const f32x4& b0, const f32x4& a1, const f32x4& b1) const {
;         float* r = hres_row(out, metah, row);
;         f32x4 v0 = (f32x4){0.f, 0.f, 0.f, 0.f}, v1 = v0, v2 = v0, v3 = v0;
;         if (r) { v0 = d.v[0] + a0; v1 = d.v[1] + b0; v2 = d.v[2] + a1; v3 = d.v[3] + b1;
;             *(f32x4*)(r + c0) = v0; *(f32x4*)(r + c0 + 4) = v1; *(f32x4*)(r + c0 + 128) = v2; *(f32x4*)(r + c0 + 132) = v3; }
.LBB0_613:
	s_or_b64 exec, exec, s[0:1]
	v_cmp_ne_u64_e32 vcc, 0, v[210:211]
	v_mov_b32_e32 v166, 0
	v_mov_b32_e32 v167, 0
	v_mov_b32_e32 v168, 0
	v_mov_b32_e32 v169, 0
	v_mov_b32_e32 v170, 0
	v_mov_b32_e32 v171, 0
	v_mov_b32_e32 v172, 0
	v_mov_b32_e32 v173, 0
	v_mov_b32_e32 v174, 0
	v_mov_b32_e32 v175, 0
	v_mov_b32_e32 v176, 0
	v_mov_b32_e32 v177, 0
	v_mov_b32_e32 v178, 0
	v_mov_b32_e32 v179, 0
	v_mov_b32_e32 v180, 0
	v_mov_b32_e32 v181, 0
	s_and_saveexec_b64 s[0:1], vcc
	s_cbranch_execz .LBB0_615
	s_waitcnt vmcnt(0)
	v_pk_add_f32 v[180:181], v[36:37], v[160:161]
	v_pk_add_f32 v[178:179], v[34:35], v[158:159]
	v_pk_add_f32 v[176:177], v[32:33], v[152:153]
	v_pk_add_f32 v[174:175], v[30:31], v[150:151]
	v_pk_add_f32 v[172:173], v[28:29], v[164:165]
	v_pk_add_f32 v[170:171], v[26:27], v[162:163]
	v_pk_add_f32 v[168:169], v[24:25], v[156:157]
	v_pk_add_f32 v[166:167], v[22:23], v[154:155]
	v_lshl_add_u64 v[150:151], v[204:205], 2, v[210:211]
	global_store_dwordx4 v[150:151], v[178:181], off nt
	global_store_dwordx4 v[150:151], v[174:177], off offset:16 nt
	global_store_dwordx4 v[150:151], v[170:173], off offset:512 nt
	global_store_dwordx4 v[150:151], v[166:169], off offset:528 nt

;     __device__ __forceinline__ void apply(const Ld& d, int row, int c0, int pn, int wc, int fq, const f32x4& a0, const f32x4& b0, const f32x4& a1, const f32x4& b1) const {
;         float* r = hres_row(out, metah, row);
;         f32x4 v0 = (f32x4){0.f, 0.f, 0.f, 0.f}, v1 = v0, v2 = v0, v3 = v0;
;         if (r) { v0 = d.v[0] + a0; v1 = d.v[1] + b0; v2 = d.v[2] + a1; v3 = d.v[3] + b1;
;             *(f32x4*)(r + c0) = v0; *(f32x4*)(r + c0 + 4) = v1; *(f32x4*)(r + c0 + 128) = v2; *(f32x4*)(r + c0 + 132) = v3; }
.LBB0_625:
	s_or_b64 exec, exec, s[0:1]
	v_cmp_ne_u64_e32 vcc, 0, v[168:169]
	v_mov_b32_e32 v154, 0
	v_mov_b32_e32 v155, 0
	v_mov_b32_e32 v156, 0
	v_mov_b32_e32 v157, 0
	v_mov_b32_e32 v150, 0
	v_mov_b32_e32 v151, 0
	v_mov_b32_e32 v152, 0
	v_mov_b32_e32 v153, 0
	v_mov_b32_e32 v158, 0
	v_mov_b32_e32 v159, 0
	v_mov_b32_e32 v160, 0
	v_mov_b32_e32 v161, 0
	v_mov_b32_e32 v162, 0
	v_mov_b32_e32 v163, 0
	v_mov_b32_e32 v164, 0
	v_mov_b32_e32 v165, 0
	s_and_saveexec_b64 s[0:1], vcc
	s_cbranch_execz .LBB0_627
	v_pk_add_f32 v[164:165], v[20:21], v[144:145]
	v_pk_add_f32 v[162:163], v[18:19], v[142:143]
	v_pk_add_f32 v[160:161], v[12:13], v[136:137]
	v_pk_add_f32 v[158:159], v[10:11], v[134:135]
	v_pk_add_f32 v[152:153], v[8:9], v[148:149]
	v_pk_add_f32 v[150:151], v[6:7], v[146:147]
	v_pk_add_f32 v[156:157], v[4:5], v[140:141]
	v_pk_add_f32 v[154:155], v[2:3], v[138:139]
	v_lshl_add_u64 v[134:135], v[204:205], 2, v[168:169]
	global_store_dwordx4 v[134:135], v[162:165], off nt
	global_store_dwordx4 v[134:135], v[158:161], off offset:16 nt
	global_store_dwordx4 v[134:135], v[150:153], off offset:512 nt
	global_store_dwordx4 v[134:135], v[154:157], off offset:528 nt
